# rwkv_fin first section: nine global inputs fetched up front with one wait (on top of v81)
# speedup vs baseline: 1.0051x; 1.0051x over previous
; __device__ __forceinline__ float bf2f(unsigned short b) { return __uint_as_float(((unsigned)b) << 16); }
; __device__ __forceinline__ float sigmoidf_(float x) { return __builtin_amdgcn_rcpf(1.0f + __expf(-x)); }
; __device__ __forceinline__ void rwkv_fin_item(const Params& p, int l, int item, char* ldsraw) {
;     ...
; #pragma unroll
;   for (int i = 0; i < 4; i++) {
;     int idx = tid + 256 * i; int t = idx >> 6, c = idx & 63;
;     int col = C_RW + 832 + c; int tok = tok0 + t;
;     float cur = bf2f(P[(size_t)tok * PIN + col]);
;     float prv = (s0 + t > 0) ? bf2f(P[(size_t)(tok - 1) * PIN + col]) : 0.f;
;     float v = cur + (prv - cur) * mu[832 + c];
;     lds[t * 64 + c] = sigmoidf_(v);
;   }
.LBB0_140:
	s_mov_b32 s2, s89
	s_add_u32 s28, s46, s2
	s_mov_b32 s3, s89
	s_mov_b32 s2, s89
	s_mov_b32 s27, s89
	s_waitcnt vmcnt(4)
	v_mov_b32_e32 v0, v198
	s_addc_u32 s29, s47, 0
	v_and_b32_e32 v57, 63, v0
	v_lshlrev_b32_e32 v2, 1, v57
	s_lshr_b32 s26, s31, 9
	s_lshl_b32 s26, s26, 7
	s_xor_b32 s26, s26, s31
	s_lshl_b32 s26, s26, 4
	v_lshl_add_u64 v[4:5], s[28:29], 0, v[2:3]
	s_mov_b64 s[28:29], 0x768b00
	v_ashrrev_i32_e32 v16, 6, v0
	v_lshl_add_u64 v[4:5], v[4:5], 0, s[28:29]
	v_add_u32_e32 v7, s26, v16
	v_mad_i64_i32 v[160:161], s[28:29], v7, s69, v[4:5]
	v_add_u32_e32 v168, -1, v7
	v_mad_i64_i32 v[162:163], s[28:29], v168, s69, v[4:5]
	v_add_u32_e32 v168, 4, v7
	v_mad_i64_i32 v[164:165], s[28:29], v168, s69, v[4:5]
	v_add_u32_e32 v168, 3, v7
	v_mad_i64_i32 v[166:167], s[28:29], v168, s69, v[4:5]
	v_add_u32_e32 v168, 8, v7
	v_mad_i64_i32 v[170:171], s[28:29], v168, s69, v[4:5]
	v_add_u32_e32 v168, 7, v7
	v_mad_i64_i32 v[172:173], s[28:29], v168, s69, v[4:5]
	v_add_u32_e32 v168, 12, v7
	v_mad_i64_i32 v[174:175], s[28:29], v168, s69, v[4:5]
	v_add_u32_e32 v168, 11, v7
	v_mad_i64_i32 v[176:177], s[28:29], v168, s69, v[4:5]
	v_lshlrev_b32_e32 v159, 2, v57
	global_load_dword v158, v159, s[24:25] offset:3328
	global_load_ushort v150, v[160:161], off
	global_load_ushort v151, v[162:163], off
	global_load_ushort v152, v[164:165], off
	global_load_ushort v153, v[166:167], off
	global_load_ushort v154, v[170:171], off
	global_load_ushort v155, v[172:173], off
	global_load_ushort v156, v[174:175], off
	global_load_ushort v157, v[176:177], off
	s_waitcnt vmcnt(0)
	v_mad_i64_i32 v[8:9], s[28:29], v7, s69, v[4:5]
	v_mov_b32_e32 v1, v150
	s_and_b32 s36, s26, 0xff0
	s_sub_i32 s37, 0, s36
	v_cmp_lt_i32_e32 vcc, s37, v16
	v_mov_b32_e32 v6, 0
	v_mov_b32_e32 v8, 0
	s_and_saveexec_b64 s[28:29], vcc
	s_cbranch_execz .LBB0_142
	v_add_u32_e32 v7, -1, v7
	v_mad_i64_i32 v[8:9], s[38:39], v7, s69, v[4:5]
	v_mov_b32_e32 v7, v151
	s_waitcnt vmcnt(0)
	v_lshlrev_b32_e32 v8, 16, v7
.LBB0_142:
	s_or_b64 exec, exec, s[28:29]
	v_lshlrev_b32_e32 v7, 2, v57
	s_waitcnt vmcnt(0)
	v_lshlrev_b32_e32 v9, 16, v1
	v_mov_b32_e32 v1, v158
	v_sub_f32_e32 v8, v8, v9
	v_lshl_add_u32 v56, v0, 2, 0
	s_waitcnt vmcnt(0)
	v_fmac_f32_e32 v9, v8, v1
	v_mul_f32_e32 v7, 0xbfb8aa3b, v9
	v_exp_f32_e32 v7, v7
	s_nop 0
	v_add_f32_e32 v7, 1.0, v7
	v_rcp_f32_e32 v7, v7
	ds_write_b32 v56, v7
	v_add_u32_e32 v7, 0x100, v0
	v_ashrrev_i32_e32 v9, 6, v7
	v_add_u32_e32 v8, s26, v9
	v_mad_i64_i32 v[10:11], s[28:29], v8, s69, v[4:5]
	v_mov_b32_e32 v7, v152
	v_cmp_lt_i32_e32 vcc, s37, v9
	s_and_saveexec_b64 s[28:29], vcc
	s_cbranch_execz .LBB0_144
	v_add_u32_e32 v6, -1, v8
	v_mad_i64_i32 v[8:9], s[38:39], v6, s69, v[4:5]
	v_mov_b32_e32 v6, v153
	s_waitcnt vmcnt(0)
	v_lshlrev_b32_e32 v6, 16, v6
.LBB0_144:
	s_or_b64 exec, exec, s[28:29]
	s_waitcnt vmcnt(0)
	v_lshlrev_b32_e32 v7, 16, v7
	v_sub_f32_e32 v6, v6, v7
	v_fmac_f32_e32 v7, v1, v6
	v_mul_f32_e32 v6, 0xbfb8aa3b, v7
	v_exp_f32_e32 v6, v6
	s_nop 0
	v_add_f32_e32 v6, 1.0, v6
	v_rcp_f32_e32 v6, v6
	ds_write_b32 v56, v6 offset:1024
	v_add_u32_e32 v6, 0x200, v0
	v_ashrrev_i32_e32 v9, 6, v6
	v_add_u32_e32 v8, s26, v9
	v_mad_i64_i32 v[6:7], s[28:29], v8, s69, v[4:5]
	v_mov_b32_e32 v7, v154
	v_cmp_lt_i32_e32 vcc, s37, v9
	v_mov_b32_e32 v6, 0
	v_mov_b32_e32 v9, 0
	s_and_saveexec_b64 s[28:29], vcc
	s_cbranch_execz .LBB0_146
	v_add_u32_e32 v8, -1, v8
	v_mad_i64_i32 v[8:9], s[38:39], v8, s69, v[4:5]
	v_mov_b32_e32 v8, v155
	s_waitcnt vmcnt(0)
	v_lshlrev_b32_e32 v9, 16, v8
.LBB0_146:
	s_or_b64 exec, exec, s[28:29]
	s_waitcnt vmcnt(0)
	v_lshlrev_b32_e32 v7, 16, v7
	v_sub_f32_e32 v8, v9, v7
	v_fmac_f32_e32 v7, v1, v8
	v_mul_f32_e32 v7, 0xbfb8aa3b, v7
	v_exp_f32_e32 v7, v7
	s_nop 0
	v_add_f32_e32 v7, 1.0, v7
	v_rcp_f32_e32 v7, v7
	ds_write_b32 v56, v7 offset:2048
	v_add_u32_e32 v7, 0x300, v0
	v_ashrrev_i32_e32 v9, 6, v7
	v_add_u32_e32 v8, s26, v9
	v_mad_i64_i32 v[10:11], s[28:29], v8, s69, v[4:5]
	v_mov_b32_e32 v7, v156
	v_cmp_lt_i32_e32 vcc, s37, v9
	s_and_saveexec_b64 s[28:29], vcc
	s_cbranch_execz .LBB0_148
	v_add_u32_e32 v6, -1, v8
	v_mad_i64_i32 v[4:5], s[38:39], v6, s69, v[4:5]
	v_mov_b32_e32 v4, v157
	s_waitcnt vmcnt(0)
	v_lshlrev_b32_e32 v6, 16, v4
